# P1 fp8 K-loop: first iteration after an epilogue peeled, its first two waits count the 16 epilogue stores (vmcnt 24)
# speedup vs baseline: 1.0134x; 1.0134x over previous
; #define PG8_STAGE_A(bufoff, off) PG8_STAGE_X(bufoff, rsA, g.A, off, voffA)
; #define PG8_STAGE_B(bufoff, off) PG8_STAGE_X(bufoff, rsB, g.Bt, off, voffB)
; #define PG8_WAIT_V(n) asm volatile("s_waitcnt vmcnt(" #n ")" ::: "memory")
; #define PG8_BAR __builtin_amdgcn_s_barrier()
; template <class Epi, class Sched, bool ALIGN_EPI, bool F8 = false>
; __device__ __forceinline__ void gemm_phase(LAS unsigned char* lds, const Gemm g, const Sched& S, const Epi& E) {
;     ...
;     const unsigned lds_w32 = (unsigned)__builtin_amdgcn_readfirstlane((int)((unsigned)(uintptr_t)lds + ldsw));
;     constexpr int KOFF = F8 ? 16 : 1024;
;     const int aoff = lds_byte(wr * 64 + fr, F8 ? fq * 16 : fq * 8), boff = lds_byte(wc * 32 + fr, F8 ? fq * 16 : fq * 8);
;     ...
;     PG8_STAGE_B(PG8_SB(0, 0), cB); PG8_STAGE_B(PG8_SB(0, 1), cB + hstepB); PG8_STAGE_A(PG8_SA(0, 0), cA); PG8_STAGE_A(PG8_SA(0, 1), cA + hstepA);
;     if (wr == 1) PG8_BAR;
;     PG8_WAIT_V(2); PG8_BAR;
;     PG8_STAGE_B(PG8_SB(1, 0), cB + kstep); PG8_STAGE_A(PG8_SA(1, 0), cA + kstep); PG8_STAGE_B(PG8_SB(1, 1), cB + hstepB + kstep);
;     PG8_WAIT_V(6); PG8_BAR;
.LBB0_577:
	s_add_i32 s55, s37, 0x18000
	s_or_b32 s2, s7, 0x80
	s_mov_b32 s28, s48
	s_mov_b32 s30, s26
	s_mov_b32 s31, s27
	s_mov_b32 m0, s55
	s_add_i32 s56, s37, 0x1a000
	s_waitcnt vmcnt(2)
	s_barrier
	buffer_load_dwordx4 v158, s[28:31], s2 offen lds
	s_mov_b32 m0, s56
	s_add_i32 s57, s37, 0x8000
	buffer_load_dwordx4 v160, s[28:31], s2 offen lds
	s_or_b32 s2, s6, 0x80
	s_mov_b32 m0, s57
	s_add_i32 s58, s37, 0xa000
	buffer_load_dwordx4 v252, s[24:27], s2 offen lds
	s_mov_b32 m0, s58
	s_add_i32 s59, s37, 0x1c000
	buffer_load_dwordx4 v159, s[24:27], s2 offen lds
	s_or_b32 s2, s7, 0x40080
	s_mov_b32 m0, s59
	s_add_i32 s60, s37, 0x1e000
	buffer_load_dwordx4 v158, s[28:31], s2 offen lds
	s_mov_b32 m0, s60
	v_bfe_u32 v1, v0, 5, 1
	buffer_load_dwordx4 v160, s[28:31], s2 offen lds
	v_lshlrev_b32_e32 v2, 1, v0
	v_lshlrev_b32_e32 v3, 6, v0
	v_lshlrev_b32_e32 v0, 2, v0
	v_and_b32_e32 v2, 32, v2
	v_and_b32_e32 v3, 0x3c0, v3
	v_and_b32_e32 v0, 32, v0
	s_sext_i32_i16 s5, s1
	s_lshl_b32 s61, s0, 6
	v_or_b32_e32 v4, v3, v2
	s_lshl_b32 s0, s0, 13
	v_lshlrev_b32_e32 v5, 10, v1
	v_bitop3_b32 v2, v3, v0, v2 bitop3:0x36
	v_readlane_b32 s1, v254, 15
	v_or3_b32 v2, v5, s0, v2
	s_lshl_b32 s0, s1, 5
	s_and_b32 s62, s0, 0x60
	s_lshr_b32 s0, s62, 3
	v_or_b32_e32 v1, s0, v1
	v_lshlrev_b32_e32 v1, 10, v1
	v_bitop3_b32 v0, v4, v1, v0 bitop3:0xde
	s_waitcnt vmcnt(6)
	s_add_i32 s64, s37, 0xc000
	s_cmp_lt_u32 s1, 4
	v_add_u32_e32 v0, 0, v0
	s_mov_b32 s63, 0
	s_cselect_b64 s[52:53], -1, 0
	s_or_b32 s65, s62, 0xffffde00
	s_add_i32 s66, s37, 0xe000
	s_ashr_i32 s67, s18, 31
	v_add_u32_e32 v161, 0x10000, v0
	v_add_u32_e32 v162, 0x14000, v0
	v_add_u32_e32 v163, 0, v2
	v_add_u32_e32 v164, 0x18000, v0
	v_add_u32_e32 v165, 0x1c000, v0
	v_mov_b32_e32 v166, 0x358637bd
	s_mov_b32 s68, 0x800000
	s_movk_i32 s69, 0x4400
	s_movk_i32 s70, 0x3000
	s_barrier
	s_mov_b32 s80, 0
	s_branch .LBB0_580

; template <class Epi, class Sched, bool ALIGN_EPI, bool F8 = false>
; __device__ __forceinline__ void gemm_phase(LAS unsigned char* lds, const Gemm g, const Sched& S, const Epi& E) {
;     ...
;         if (!has_next) break;
; #pragma unroll
;         for (int a = 0; a < 2; ++a)
; #pragma unroll
;             for (int b = 0; b < 2; ++b)
; #pragma unroll
;                 for (int m = 0; m < 4; ++m)
; #pragma unroll
;                     for (int n = 0; n < 2; ++n) acc[a][b][m][n] = (f32x4){0.f, 0.f, 0.f, 0.f};
;         cur = nxt; cA = nA; cB = nB; ++ui;
.LBB0_579:
	s_mov_b32 s80, 1
	s_andn2_b64 vcc, exec, s[0:1]
	s_mov_b32 s4, s72
	s_mov_b32 s5, s71
	s_mov_b32 s7, s74
	s_mov_b32 s6, s73
	s_cbranch_vccz .LBB0_597

; #define PG8_STAGE_A(bufoff, off) PG8_STAGE_X(bufoff, rsA, g.A, off, voffA)
; #define PG8_LDA(dst, b, h) do { _Pragma("unroll") for (int m = 0; m < 4; ++m) _Pragma("unroll") for (int k = 0; k < 2; ++k) { const v4i_t f_ = *(const LAS v4i_t*)(lds + PG8_SA(b, h) + aoff + m * 2048 + k * KOFF); dst[m][4 * k] = f_[0]; dst[m][4 * k + 1] = f_[1]; dst[m][4 * k + 2] = f_[2]; dst[m][4 * k + 3] = f_[3]; } } while (0)
; #define PG8_LDB(dst, b, h) do { _Pragma("unroll") for (int n = 0; n < 2; ++n) _Pragma("unroll") for (int k = 0; k < 2; ++k) { const v4i_t f_ = *(const LAS v4i_t*)(lds + PG8_SB(b, h) + boff + n * 2048 + k * KOFF); dst[n][4 * k] = f_[0]; dst[n][4 * k + 1] = f_[1]; dst[n][4 * k + 2] = f_[2]; dst[n][4 * k + 3] = f_[3]; } } while (0)
; #define PG8_WAIT_V(n) asm volatile("s_waitcnt vmcnt(" #n ")" ::: "memory")
; #define PG8_WAIT_L(n) asm volatile("s_waitcnt lgkmcnt(" #n ")" ::: "memory")
; #define PG8_BAR __builtin_amdgcn_s_barrier()
; #define PG8_SCHED __builtin_amdgcn_sched_barrier(0)
; template <class Epi, class Sched, bool ALIGN_EPI, bool F8 = false>
; __device__ __forceinline__ void gemm_phase(LAS unsigned char* lds, const Gemm g, const Sched& S, const Epi& E) {
;     ...
;         for (int t = 0; t < nt; t += 2) {
;             const bool last = (t == nt - 2);
;             const unsigned a1 = cA + (unsigned)(t + 1) * kstep;
;             const unsigned a2 = last ? nA : cA + (unsigned)(t + 2) * kstep; const unsigned b2 = last ? nB : cB + (unsigned)(t + 2) * kstep;
;             const unsigned a3 = a2 + kstep; const unsigned b3 = b2 + kstep;
;             PG8_LDB(B0, 0, 0); PG8_LDB(B1, 0, 1); PG8_SCHED; PG8_LDA(At, 0, 0); PG8_STAGE_A(PG8_SA(1, 1), a1 + hstepA);
;             PG8_WAIT_V(8); PG8_WAIT_L(0); PG8_BAR; PG8_MMA(0, 0, At, B0); PG8_MMA(0, 1, At, B1); PG8_BAR; PG8_SCHED;
;     ...
;         for (int a = 0; a < 2; ++a)
; #pragma unroll
;             for (int b = 0; b < 2; ++b)
; #pragma unroll
;                 for (int m = 0; m < 4; ++m)
; #pragma unroll
;                     for (int n = 0; n < 2; ++n) acc[a][b][m][n] = (f32x4){0.f, 0.f, 0.f, 0.f};
.LBB0_582:
	s_lshl_b32 s73, s71, 19
	s_and_b64 s[0:1], s[2:3], exec
	s_cselect_b32 s0, s73, s6
	s_lshl_b32 s74, s72, 19
	s_and_b64 s[8:9], s[2:3], exec
	v_mov_b32_e32 v0, 0
	s_cselect_b32 s1, s74, s7
	s_add_i32 s6, s6, 0x40080
	s_addk_i32 s7, 0x100
	s_mov_b32 s8, -2
	v_mov_b32_e32 v1, v0
	v_mov_b32_e32 v2, v0
	v_mov_b32_e32 v3, v0
	v_mov_b32_e32 v4, v0
	v_mov_b32_e32 v5, v0
	v_mov_b32_e32 v6, v0
	v_mov_b32_e32 v7, v0
	v_mov_b32_e32 v16, v0
	v_mov_b32_e32 v17, v0
	v_mov_b32_e32 v18, v0
	v_mov_b32_e32 v19, v0
	v_mov_b32_e32 v20, v0
	v_mov_b32_e32 v21, v0
	v_mov_b32_e32 v22, v0
	v_mov_b32_e32 v23, v0
	v_mov_b32_e32 v32, v0
	v_mov_b32_e32 v33, v0
	v_mov_b32_e32 v34, v0
	v_mov_b32_e32 v35, v0
	v_mov_b32_e32 v36, v0
	v_mov_b32_e32 v37, v0
	v_mov_b32_e32 v38, v0
	v_mov_b32_e32 v39, v0
	v_mov_b32_e32 v48, v0
	v_mov_b32_e32 v49, v0
	v_mov_b32_e32 v50, v0
	v_mov_b32_e32 v51, v0
	v_mov_b32_e32 v52, v0
	v_mov_b32_e32 v53, v0
	v_mov_b32_e32 v54, v0
	v_mov_b32_e32 v55, v0
	v_mov_b32_e32 v8, v0
	v_mov_b32_e32 v9, v0
	v_mov_b32_e32 v10, v0
	v_mov_b32_e32 v11, v0
	v_mov_b32_e32 v12, v0
	v_mov_b32_e32 v13, v0
	v_mov_b32_e32 v14, v0
	v_mov_b32_e32 v15, v0
	v_mov_b32_e32 v24, v0
	v_mov_b32_e32 v25, v0
	v_mov_b32_e32 v26, v0
	v_mov_b32_e32 v27, v0
	v_mov_b32_e32 v28, v0
	v_mov_b32_e32 v29, v0
	v_mov_b32_e32 v30, v0
	v_mov_b32_e32 v31, v0
	v_mov_b32_e32 v40, v0
	v_mov_b32_e32 v41, v0
	v_mov_b32_e32 v42, v0
	v_mov_b32_e32 v43, v0
	v_mov_b32_e32 v44, v0
	v_mov_b32_e32 v45, v0
	v_mov_b32_e32 v46, v0
	v_mov_b32_e32 v47, v0
	v_mov_b32_e32 v56, v0
	v_mov_b32_e32 v57, v0
	v_mov_b32_e32 v58, v0
	v_mov_b32_e32 v59, v0
	v_mov_b32_e32 v60, v0
	v_mov_b32_e32 v61, v0
	v_mov_b32_e32 v62, v0
	v_mov_b32_e32 v63, v0
	v_mov_b32_e32 v64, v0
	v_mov_b32_e32 v65, v0
	v_mov_b32_e32 v66, v0
	v_mov_b32_e32 v67, v0
	v_mov_b32_e32 v68, v0
	v_mov_b32_e32 v69, v0
	v_mov_b32_e32 v70, v0
	v_mov_b32_e32 v71, v0
	v_mov_b32_e32 v80, v0
	v_mov_b32_e32 v81, v0
	v_mov_b32_e32 v82, v0
	v_mov_b32_e32 v83, v0
	v_mov_b32_e32 v84, v0
	v_mov_b32_e32 v85, v0
	v_mov_b32_e32 v86, v0
	v_mov_b32_e32 v87, v0
	v_mov_b32_e32 v96, v0
	v_mov_b32_e32 v97, v0
	v_mov_b32_e32 v98, v0
	v_mov_b32_e32 v99, v0
	v_mov_b32_e32 v100, v0
	v_mov_b32_e32 v101, v0
	v_mov_b32_e32 v102, v0
	v_mov_b32_e32 v103, v0
	v_mov_b32_e32 v112, v0
	v_mov_b32_e32 v113, v0
	v_mov_b32_e32 v114, v0
	v_mov_b32_e32 v115, v0
	v_mov_b32_e32 v116, v0
	v_mov_b32_e32 v117, v0
	v_mov_b32_e32 v118, v0
	v_mov_b32_e32 v119, v0
	v_mov_b32_e32 v72, v0
	v_mov_b32_e32 v73, v0
	v_mov_b32_e32 v74, v0
	v_mov_b32_e32 v75, v0
	v_mov_b32_e32 v76, v0
	v_mov_b32_e32 v77, v0
	v_mov_b32_e32 v78, v0
	v_mov_b32_e32 v79, v0
	v_mov_b32_e32 v88, v0
	v_mov_b32_e32 v89, v0
	v_mov_b32_e32 v90, v0
	v_mov_b32_e32 v91, v0
	v_mov_b32_e32 v92, v0
	v_mov_b32_e32 v93, v0
	v_mov_b32_e32 v94, v0
	v_mov_b32_e32 v95, v0
	v_mov_b32_e32 v104, v0
	v_mov_b32_e32 v105, v0
	v_mov_b32_e32 v106, v0
	v_mov_b32_e32 v107, v0
	v_mov_b32_e32 v108, v0
	v_mov_b32_e32 v109, v0
	v_mov_b32_e32 v110, v0
	v_mov_b32_e32 v111, v0
	v_mov_b32_e32 v120, v0
	v_mov_b32_e32 v121, v0
	v_mov_b32_e32 v122, v0
	v_mov_b32_e32 v123, v0
	v_mov_b32_e32 v124, v0
	v_mov_b32_e32 v125, v0
	v_mov_b32_e32 v126, v0
	v_mov_b32_e32 v127, v0
	s_cmp_lg_u32 s80, 0
	s_cbranch_scc0 .LBB0_583
	ds_read_b128 v[136:139], v161
	ds_read_b128 v[140:143], v161 offset:16
	ds_read_b128 v[168:171], v161 offset:2048
	ds_read_b128 v[172:175], v161 offset:2064
	ds_read_b128 v[176:179], v162
	ds_read_b128 v[180:183], v162 offset:16
	ds_read_b128 v[184:187], v162 offset:2048
	ds_read_b128 v[188:191], v162 offset:2064
	s_add_i32 s9, s6, 0xfffc0080
	s_cmp_eq_u32 s8, 12
	s_cselect_b32 s11, s0, s9
	s_cselect_b32 s10, s1, s7
	s_or_b32 s9, s11, 0x80
	s_mov_b32 m0, s64
	ds_read_b128 v[192:195], v163
	ds_read_b128 v[196:199], v163 offset:16
	ds_read_b128 v[200:203], v163 offset:2048
	ds_read_b128 v[204:207], v163 offset:2064
	ds_read_b128 v[208:211], v163 offset:4096
	ds_read_b128 v[212:215], v163 offset:4112
	ds_read_b128 v[216:219], v163 offset:6144
	ds_read_b128 v[220:223], v163 offset:6160
	buffer_load_dwordx4 v252, s[24:27], s6 offen lds
	s_mov_b32 m0, s66
	s_nop 0
	buffer_load_dwordx4 v159, s[24:27], s6 offen lds
	s_waitcnt vmcnt(24)
	s_waitcnt lgkmcnt(0)
	s_barrier
	s_setprio 1
	s_waitcnt lgkmcnt(0)
	v_mfma_f32_16x16x128_f8f6f4 v[124:127], v[136:143], v[192:199], v[124:127]
	v_mfma_f32_16x16x128_f8f6f4 v[120:123], v[168:175], v[192:199], v[120:123]
	v_mfma_f32_16x16x128_f8f6f4 v[108:111], v[136:143], v[200:207], v[108:111]
	v_mfma_f32_16x16x128_f8f6f4 v[104:107], v[168:175], v[200:207], v[104:107]
	v_mfma_f32_16x16x128_f8f6f4 v[128:131], v[136:143], v[208:215], v[92:95]
	v_mfma_f32_16x16x128_f8f6f4 v[144:147], v[168:175], v[208:215], v[88:91]
	v_mfma_f32_16x16x128_f8f6f4 v[150:153], v[136:143], v[216:223], v[76:79]
	v_mfma_f32_16x16x128_f8f6f4 v[224:227], v[168:175], v[216:223], v[72:75]
	s_setprio 0
	s_setprio 1
	v_mfma_f32_16x16x128_f8f6f4 v[116:119], v[176:183], v[192:199], v[116:119]
	v_mfma_f32_16x16x128_f8f6f4 v[112:115], v[184:191], v[192:199], v[112:115]
	v_mfma_f32_16x16x128_f8f6f4 v[100:103], v[176:183], v[200:207], v[100:103]
	v_mfma_f32_16x16x128_f8f6f4 v[96:99], v[184:191], v[200:207], v[96:99]
	v_mfma_f32_16x16x128_f8f6f4 v[192:195], v[176:183], v[208:215], v[84:87]
	v_mfma_f32_16x16x128_f8f6f4 v[196:199], v[184:191], v[208:215], v[80:83]
	v_mfma_f32_16x16x128_f8f6f4 v[200:203], v[176:183], v[216:223], v[68:71]
	v_mfma_f32_16x16x128_f8f6f4 v[204:207], v[184:191], v[216:223], v[64:67]
	s_setprio 0
	s_barrier
; #define PG8_STAGE_A(bufoff, off) PG8_STAGE_X(bufoff, rsA, g.A, off, voffA)
; #define PG8_STAGE_B(bufoff, off) PG8_STAGE_X(bufoff, rsB, g.Bt, off, voffB)
; #define PG8_LDA(dst, b, h) do { _Pragma("unroll") for (int m = 0; m < 4; ++m) _Pragma("unroll") for (int k = 0; k < 2; ++k) { const v4i_t f_ = *(const LAS v4i_t*)(lds + PG8_SA(b, h) + aoff + m * 2048 + k * KOFF); dst[m][4 * k] = f_[0]; dst[m][4 * k + 1] = f_[1]; dst[m][4 * k + 2] = f_[2]; dst[m][4 * k + 3] = f_[3]; } } while (0)
; #define PG8_LDB(dst, b, h) do { _Pragma("unroll") for (int n = 0; n < 2; ++n) _Pragma("unroll") for (int k = 0; k < 2; ++k) { const v4i_t f_ = *(const LAS v4i_t*)(lds + PG8_SB(b, h) + boff + n * 2048 + k * KOFF); dst[n][4 * k] = f_[0]; dst[n][4 * k + 1] = f_[1]; dst[n][4 * k + 2] = f_[2]; dst[n][4 * k + 3] = f_[3]; } } while (0)
; #define PG8_WAIT_V(n) asm volatile("s_waitcnt vmcnt(" #n ")" ::: "memory")
; #define PG8_WAIT_L(n) asm volatile("s_waitcnt lgkmcnt(" #n ")" ::: "memory")
; #define PG8_BAR __builtin_amdgcn_s_barrier()
; #define PG8_SCHED __builtin_amdgcn_sched_barrier(0)
; template <class Epi, class Sched, bool ALIGN_EPI, bool F8 = false>
; __device__ __forceinline__ void gemm_phase(LAS unsigned char* lds, const Gemm g, const Sched& S, const Epi& E) {
;     ...
;             PG8_LDA(At, 0, 1); PG8_STAGE_B(PG8_SB(0, 0), b2); PG8_STAGE_B(PG8_SB(0, 1), b2 + hstepB); PG8_STAGE_A(PG8_SA(0, 0), a2);
;             PG8_WAIT_V(8); PG8_WAIT_L(0); PG8_BAR; PG8_MMA(1, 0, At, B0); PG8_MMA(1, 1, At, B1); PG8_BAR; PG8_SCHED;
;             PG8_LDB(B0, 1, 0); PG8_LDB(B1, 1, 1); PG8_SCHED; PG8_LDA(At, 1, 0); PG8_STAGE_A(PG8_SA(0, 1), a2 + hstepA);
;             PG8_WAIT_V(8); PG8_WAIT_L(0); PG8_BAR; PG8_MMA(0, 0, At, B0); PG8_MMA(0, 1, At, B1); PG8_BAR; PG8_SCHED;
;             PG8_LDA(At, 1, 1); PG8_STAGE_B(PG8_SB(1, 0), b3); PG8_STAGE_B(PG8_SB(1, 1), b3 + hstepB); PG8_STAGE_A(PG8_SA(1, 0), a3);
;             PG8_WAIT_V(8); PG8_WAIT_L(0); PG8_BAR; PG8_MMA(1, 0, At, B0); PG8_MMA(1, 1, At, B1); PG8_BAR; PG8_SCHED;
	s_mov_b32 m0, s38
	s_mov_b32 s28, s48
	s_mov_b32 s30, s26
	s_mov_b32 s31, s27
	s_nop 0
	ds_read_b128 v[64:67], v163 offset:16384
	ds_read_b128 v[68:71], v163 offset:16400
	ds_read_b128 v[72:75], v163 offset:18432
	ds_read_b128 v[76:79], v163 offset:18448
	ds_read_b128 v[80:83], v163 offset:20480
	ds_read_b128 v[84:87], v163 offset:20496
	ds_read_b128 v[88:91], v163 offset:22528
	ds_read_b128 v[92:95], v163 offset:22544
	buffer_load_dwordx4 v158, s[28:31], s10 offen lds
	s_mov_b32 m0, s39
	s_add_i32 s12, s10, 0x40000
	buffer_load_dwordx4 v160, s[28:31], s10 offen lds
	s_mov_b32 m0, s40
	s_nop 0
	buffer_load_dwordx4 v158, s[28:31], s12 offen lds
	s_mov_b32 m0, s41
	s_nop 0
	buffer_load_dwordx4 v160, s[28:31], s12 offen lds
	s_mov_b32 m0, s37
	s_nop 0
	buffer_load_dwordx4 v252, s[24:27], s11 offen lds
	s_mov_b32 m0, s42
	s_nop 0
	buffer_load_dwordx4 v159, s[24:27], s11 offen lds
	s_waitcnt vmcnt(24)
	s_waitcnt lgkmcnt(0)
	s_barrier
	s_setprio 1
	s_waitcnt lgkmcnt(0)
	v_mfma_f32_16x16x128_f8f6f4 v[60:63], v[136:143], v[64:71], v[60:63]
	v_mfma_f32_16x16x128_f8f6f4 v[56:59], v[168:175], v[64:71], v[56:59]
	v_mfma_f32_16x16x128_f8f6f4 v[208:211], v[136:143], v[72:79], v[44:47]
	v_mfma_f32_16x16x128_f8f6f4 v[212:215], v[168:175], v[72:79], v[40:43]
	v_mfma_f32_16x16x128_f8f6f4 v[216:219], v[136:143], v[80:87], v[28:31]
	v_mfma_f32_16x16x128_f8f6f4 v[220:223], v[168:175], v[80:87], v[24:27]
	v_mfma_f32_16x16x128_f8f6f4 v[228:231], v[136:143], v[88:95], v[12:15]
	v_mfma_f32_16x16x128_f8f6f4 v[232:235], v[168:175], v[88:95], v[8:11]
	s_setprio 0
	s_setprio 1
	v_mfma_f32_16x16x128_f8f6f4 v[52:55], v[176:183], v[64:71], v[52:55]
	v_mfma_f32_16x16x128_f8f6f4 v[48:51], v[184:191], v[64:71], v[48:51]
	v_mfma_f32_16x16x128_f8f6f4 v[236:239], v[176:183], v[72:79], v[36:39]
	v_mfma_f32_16x16x128_f8f6f4 v[240:243], v[184:191], v[72:79], v[32:35]
	v_mfma_f32_16x16x128_f8f6f4 v[244:247], v[176:183], v[80:87], v[20:23]
	v_mfma_f32_16x16x128_f8f6f4 v[248:251], v[184:191], v[80:87], v[16:19]
	v_mfma_f32_16x16x128_f8f6f4 v[132:135], v[176:183], v[88:95], v[4:7]
	v_mfma_f32_16x16x128_f8f6f4 v[154:157], v[184:191], v[88:95], v[0:3]
	s_setprio 0
	s_barrier
	s_nop 4
	ds_read_b128 v[0:3], v164
	ds_read_b128 v[4:7], v164 offset:16
	ds_read_b128 v[16:19], v164 offset:2048
	ds_read_b128 v[20:23], v164 offset:2064
	ds_read_b128 v[136:139], v165
	ds_read_b128 v[140:143], v165 offset:16
	ds_read_b128 v[168:171], v165 offset:2048
	ds_read_b128 v[172:175], v165 offset:2064
	s_add_i32 s11, s11, 0x40000
	s_mov_b32 m0, s43
	ds_read_b128 v[8:11], v163 offset:32768
	ds_read_b128 v[12:15], v163 offset:32784
	ds_read_b128 v[24:27], v163 offset:34816
	ds_read_b128 v[28:31], v163 offset:34832
	ds_read_b128 v[32:35], v163 offset:36864
	ds_read_b128 v[36:39], v163 offset:36880
	ds_read_b128 v[40:43], v163 offset:38912
	ds_read_b128 v[44:47], v163 offset:38928
	buffer_load_dwordx4 v252, s[24:27], s11 offen lds
	s_mov_b32 m0, s54
	s_nop 0
	buffer_load_dwordx4 v159, s[24:27], s11 offen lds
	s_waitcnt vmcnt(8)
	s_waitcnt lgkmcnt(0)
	s_barrier
	s_setprio 1
	s_waitcnt lgkmcnt(0)
	v_mfma_f32_16x16x128_f8f6f4 v[124:127], v[0:7], v[8:15], v[124:127]
	v_mfma_f32_16x16x128_f8f6f4 v[120:123], v[16:23], v[8:15], v[120:123]
	v_mfma_f32_16x16x128_f8f6f4 v[108:111], v[0:7], v[24:31], v[108:111]
	v_mfma_f32_16x16x128_f8f6f4 v[104:107], v[16:23], v[24:31], v[104:107]
	v_mfma_f32_16x16x128_f8f6f4 v[92:95], v[0:7], v[32:39], v[128:131]
	v_mfma_f32_16x16x128_f8f6f4 v[88:91], v[16:23], v[32:39], v[144:147]
	v_mfma_f32_16x16x128_f8f6f4 v[76:79], v[0:7], v[40:47], v[150:153]
	v_mfma_f32_16x16x128_f8f6f4 v[72:75], v[16:23], v[40:47], v[224:227]
	s_setprio 0
	s_setprio 1
	v_mfma_f32_16x16x128_f8f6f4 v[116:119], v[136:143], v[8:15], v[116:119]
	v_mfma_f32_16x16x128_f8f6f4 v[112:115], v[168:175], v[8:15], v[112:115]
	v_mfma_f32_16x16x128_f8f6f4 v[100:103], v[136:143], v[24:31], v[100:103]
	v_mfma_f32_16x16x128_f8f6f4 v[96:99], v[168:175], v[24:31], v[96:99]
	v_mfma_f32_16x16x128_f8f6f4 v[84:87], v[136:143], v[32:39], v[192:195]
	v_mfma_f32_16x16x128_f8f6f4 v[80:83], v[168:175], v[32:39], v[196:199]
	v_mfma_f32_16x16x128_f8f6f4 v[68:71], v[136:143], v[40:47], v[200:203]
	v_mfma_f32_16x16x128_f8f6f4 v[64:67], v[168:175], v[40:47], v[204:207]
	s_setprio 0
	s_barrier
	s_mov_b32 m0, s55
	s_or_b32 s11, s10, 0x80
	ds_read_b128 v[32:35], v163 offset:49152
	ds_read_b128 v[36:39], v163 offset:49168
	ds_read_b128 v[176:179], v163 offset:51200
	ds_read_b128 v[180:183], v163 offset:51216
	ds_read_b128 v[184:187], v163 offset:53248
	ds_read_b128 v[188:191], v163 offset:53264
	ds_read_b128 v[192:195], v163 offset:55296
	ds_read_b128 v[196:199], v163 offset:55312
	buffer_load_dwordx4 v158, s[28:31], s11 offen lds
	s_mov_b32 m0, s56
	s_add_i32 s10, s10, 0x40080
	buffer_load_dwordx4 v160, s[28:31], s11 offen lds
	s_mov_b32 m0, s59
	s_nop 0
	buffer_load_dwordx4 v158, s[28:31], s10 offen lds
	s_mov_b32 m0, s60
	s_nop 0
	buffer_load_dwordx4 v160, s[28:31], s10 offen lds
	s_mov_b32 m0, s57
	s_nop 0
	buffer_load_dwordx4 v252, s[24:27], s9 offen lds
	s_mov_b32 m0, s58
	s_nop 0
	buffer_load_dwordx4 v159, s[24:27], s9 offen lds
	s_waitcnt vmcnt(8)
	s_waitcnt lgkmcnt(0)
	s_barrier
	s_setprio 1
	s_waitcnt lgkmcnt(0)
	v_mfma_f32_16x16x128_f8f6f4 v[60:63], v[0:7], v[32:39], v[60:63]
	v_mfma_f32_16x16x128_f8f6f4 v[56:59], v[16:23], v[32:39], v[56:59]
	v_mfma_f32_16x16x128_f8f6f4 v[44:47], v[0:7], v[176:183], v[208:211]
	v_mfma_f32_16x16x128_f8f6f4 v[40:43], v[16:23], v[176:183], v[212:215]
	v_mfma_f32_16x16x128_f8f6f4 v[28:31], v[0:7], v[184:191], v[216:219]
	v_mfma_f32_16x16x128_f8f6f4 v[24:27], v[16:23], v[184:191], v[220:223]
	v_mfma_f32_16x16x128_f8f6f4 v[12:15], v[0:7], v[192:199], v[228:231]
	v_mfma_f32_16x16x128_f8f6f4 v[8:11], v[16:23], v[192:199], v[232:235]
	s_setprio 0
	s_setprio 1
	v_mfma_f32_16x16x128_f8f6f4 v[52:55], v[136:143], v[32:39], v[52:55]
	v_mfma_f32_16x16x128_f8f6f4 v[48:51], v[168:175], v[32:39], v[48:51]
	v_mfma_f32_16x16x128_f8f6f4 v[36:39], v[136:143], v[176:183], v[236:239]
	v_mfma_f32_16x16x128_f8f6f4 v[32:35], v[168:175], v[176:183], v[240:243]
	v_mfma_f32_16x16x128_f8f6f4 v[20:23], v[136:143], v[184:191], v[244:247]
	v_mfma_f32_16x16x128_f8f6f4 v[16:19], v[168:175], v[184:191], v[248:251]
	v_mfma_f32_16x16x128_f8f6f4 v[4:7], v[136:143], v[192:199], v[132:135]
	v_mfma_f32_16x16x128_f8f6f4 v[0:3], v[168:175], v[192:199], v[154:157]
	s_setprio 0
	s_barrier
	s_add_i32 s8, s8, 2
	s_addk_i32 s6, 0x100
	s_addk_i32 s7, 0x100
	s_cmp_gt_u32 s8, 13
	s_cbranch_scc0 .LBB0_583
	s_branch .Lpeel_after_pl0

; #define PG8_BAR __builtin_amdgcn_s_barrier()
; template <class Epi, class Sched, bool ALIGN_EPI, bool F8 = false>
; __device__ __forceinline__ void gemm_phase(LAS unsigned char* lds, const Gemm g, const Sched& S, const Epi& E) {
;     ...
;         if constexpr (ALIGN_EPI) { if (wr == 0) PG8_BAR; }
.Lpeel_after_pl0:
	s_and_b64 vcc, exec, s[52:53]
	s_cbranch_vccz .LBB0_586
	s_barrier

; #define PG8_STAGE_A(bufoff, off) PG8_STAGE_X(bufoff, rsA, g.A, off, voffA)
; #define PG8_STAGE_B(bufoff, off) PG8_STAGE_X(bufoff, rsB, g.Bt, off, voffB)
; #define PG8_WAIT_V(n) asm volatile("s_waitcnt vmcnt(" #n ")" ::: "memory")
; #define PG8_BAR __builtin_amdgcn_s_barrier()
; template <class Epi, class Sched, bool ALIGN_EPI, bool F8 = false>
; __device__ __forceinline__ void gemm_phase(LAS unsigned char* lds, const Gemm g, const Sched& S, const Epi& E) {
;     ...
;     const unsigned lds_w32 = (unsigned)__builtin_amdgcn_readfirstlane((int)((unsigned)(uintptr_t)lds + ldsw));
;     constexpr int KOFF = F8 ? 16 : 1024;
;     const int aoff = lds_byte(wr * 64 + fr, F8 ? fq * 16 : fq * 8), boff = lds_byte(wc * 32 + fr, F8 ? fq * 16 : fq * 8);
;     ...
;     PG8_STAGE_B(PG8_SB(0, 0), cB); PG8_STAGE_B(PG8_SB(0, 1), cB + hstepB); PG8_STAGE_A(PG8_SA(0, 0), cA); PG8_STAGE_A(PG8_SA(0, 1), cA + hstepA);
;     if (wr == 1) PG8_BAR;
;     PG8_WAIT_V(2); PG8_BAR;
;     PG8_STAGE_B(PG8_SB(1, 0), cB + kstep); PG8_STAGE_A(PG8_SA(1, 0), cA + kstep); PG8_STAGE_B(PG8_SB(1, 1), cB + hstepB + kstep);
;     PG8_WAIT_V(6); PG8_BAR;
.LBB0_1429:
	s_add_i32 s55, s37, 0x18000
	s_or_b32 s2, s7, 0x80
	s_mov_b32 s26, s30
	s_mov_b32 s27, s31
	s_mov_b32 m0, s55
	s_add_i32 s56, s37, 0x1a000
	s_waitcnt vmcnt(2)
	s_barrier
	buffer_load_dwordx4 v158, s[24:27], s2 offen lds
	s_mov_b32 m0, s56
	s_add_i32 s57, s37, 0x8000
	buffer_load_dwordx4 v160, s[24:27], s2 offen lds
	s_or_b32 s2, s6, 0x80
	s_mov_b32 m0, s57
	s_add_i32 s58, s37, 0xa000
	buffer_load_dwordx4 v252, s[28:31], s2 offen lds
	s_mov_b32 m0, s58
	s_add_i32 s59, s37, 0x1c000
	buffer_load_dwordx4 v159, s[28:31], s2 offen lds
	s_or_b32 s2, s7, 0x40080
	s_mov_b32 m0, s59
	s_add_i32 s60, s37, 0x1e000
	buffer_load_dwordx4 v158, s[24:27], s2 offen lds
	s_mov_b32 m0, s60
	v_bfe_u32 v1, v0, 5, 1
	buffer_load_dwordx4 v160, s[24:27], s2 offen lds
	v_lshlrev_b32_e32 v2, 1, v0
	v_lshlrev_b32_e32 v3, 6, v0
	v_lshlrev_b32_e32 v0, 2, v0
	v_and_b32_e32 v2, 32, v2
	v_and_b32_e32 v3, 0x3c0, v3
	v_and_b32_e32 v0, 32, v0
	s_sext_i32_i16 s5, s1
	s_lshl_b32 s61, s0, 6
	v_or_b32_e32 v4, v3, v2
	s_lshl_b32 s0, s0, 13
	v_lshlrev_b32_e32 v5, 10, v1
	v_bitop3_b32 v2, v3, v0, v2 bitop3:0x36
	v_readlane_b32 s1, v254, 15
	v_or3_b32 v2, v5, s0, v2
	s_lshl_b32 s0, s1, 5
	s_and_b32 s62, s0, 0x60
	s_lshr_b32 s0, s62, 3
	v_or_b32_e32 v1, s0, v1
	v_lshlrev_b32_e32 v1, 10, v1
	v_bitop3_b32 v0, v4, v1, v0 bitop3:0xde
	s_waitcnt vmcnt(6)
	s_add_i32 s64, s37, 0xc000
	s_cmp_lt_u32 s1, 4
	v_add_u32_e32 v0, 0, v0
	s_mov_b32 s63, 0
	s_cselect_b64 s[52:53], -1, 0
	s_or_b32 s65, s62, 0xffffde00
	s_add_i32 s66, s37, 0xe000
	s_ashr_i32 s67, s18, 31
	v_add_u32_e32 v161, 0x10000, v0
	v_add_u32_e32 v162, 0x14000, v0
	v_add_u32_e32 v163, 0, v2
	v_add_u32_e32 v164, 0x18000, v0
	v_add_u32_e32 v165, 0x1c000, v0
	v_mov_b32_e32 v166, 0x358637bd
	s_mov_b32 s68, 0x800000
	s_movk_i32 s69, 0x4400
	s_movk_i32 s70, 0x3000
	s_barrier
	s_mov_b32 s80, 0
	s_branch .LBB0_1432

; #define PG8_STAGE_A(bufoff, off) PG8_STAGE_X(bufoff, rsA, g.A, off, voffA)
; #define PG8_LDA(dst, b, h) do { _Pragma("unroll") for (int m = 0; m < 4; ++m) _Pragma("unroll") for (int k = 0; k < 2; ++k) { const v4i_t f_ = *(const LAS v4i_t*)(lds + PG8_SA(b, h) + aoff + m * 2048 + k * KOFF); dst[m][4 * k] = f_[0]; dst[m][4 * k + 1] = f_[1]; dst[m][4 * k + 2] = f_[2]; dst[m][4 * k + 3] = f_[3]; } } while (0)
; #define PG8_LDB(dst, b, h) do { _Pragma("unroll") for (int n = 0; n < 2; ++n) _Pragma("unroll") for (int k = 0; k < 2; ++k) { const v4i_t f_ = *(const LAS v4i_t*)(lds + PG8_SB(b, h) + boff + n * 2048 + k * KOFF); dst[n][4 * k] = f_[0]; dst[n][4 * k + 1] = f_[1]; dst[n][4 * k + 2] = f_[2]; dst[n][4 * k + 3] = f_[3]; } } while (0)
; #define PG8_WAIT_V(n) asm volatile("s_waitcnt vmcnt(" #n ")" ::: "memory")
; #define PG8_WAIT_L(n) asm volatile("s_waitcnt lgkmcnt(" #n ")" ::: "memory")
; #define PG8_BAR __builtin_amdgcn_s_barrier()
; #define PG8_SCHED __builtin_amdgcn_sched_barrier(0)
; template <class Epi, class Sched, bool ALIGN_EPI, bool F8 = false>
; __device__ __forceinline__ void gemm_phase(LAS unsigned char* lds, const Gemm g, const Sched& S, const Epi& E) {
;     ...
;         for (int t = 0; t < nt; t += 2) {
;             const bool last = (t == nt - 2);
;             const unsigned a1 = cA + (unsigned)(t + 1) * kstep;
;             const unsigned a2 = last ? nA : cA + (unsigned)(t + 2) * kstep; const unsigned b2 = last ? nB : cB + (unsigned)(t + 2) * kstep;
;             const unsigned a3 = a2 + kstep; const unsigned b3 = b2 + kstep;
;             PG8_LDB(B0, 0, 0); PG8_LDB(B1, 0, 1); PG8_SCHED; PG8_LDA(At, 0, 0); PG8_STAGE_A(PG8_SA(1, 1), a1 + hstepA);
;             PG8_WAIT_V(8); PG8_WAIT_L(0); PG8_BAR; PG8_MMA(0, 0, At, B0); PG8_MMA(0, 1, At, B1); PG8_BAR; PG8_SCHED;
;     ...
;         for (int a = 0; a < 2; ++a)
; #pragma unroll
;             for (int b = 0; b < 2; ++b)
; #pragma unroll
;                 for (int m = 0; m < 4; ++m)
; #pragma unroll
;                     for (int n = 0; n < 2; ++n) acc[a][b][m][n] = (f32x4){0.f, 0.f, 0.f, 0.f};
.LBB0_1434:
	s_lshl_b32 s73, s71, 19
	s_and_b64 s[0:1], s[2:3], exec
	s_cselect_b32 s0, s73, s6
	s_lshl_b32 s74, s72, 19
	s_and_b64 s[8:9], s[2:3], exec
	v_mov_b32_e32 v0, 0
	s_cselect_b32 s1, s74, s7
	s_add_i32 s6, s6, 0x40080
	s_addk_i32 s7, 0x100
	s_mov_b32 s8, -2
	v_mov_b32_e32 v1, v0
	v_mov_b32_e32 v2, v0
	v_mov_b32_e32 v3, v0
	v_mov_b32_e32 v4, v0
	v_mov_b32_e32 v5, v0
	v_mov_b32_e32 v6, v0
	v_mov_b32_e32 v7, v0
	v_mov_b32_e32 v16, v0
	v_mov_b32_e32 v17, v0
	v_mov_b32_e32 v18, v0
	v_mov_b32_e32 v19, v0
	v_mov_b32_e32 v20, v0
	v_mov_b32_e32 v21, v0
	v_mov_b32_e32 v22, v0
	v_mov_b32_e32 v23, v0
	v_mov_b32_e32 v32, v0
	v_mov_b32_e32 v33, v0
	v_mov_b32_e32 v34, v0
	v_mov_b32_e32 v35, v0
	v_mov_b32_e32 v36, v0
	v_mov_b32_e32 v37, v0
	v_mov_b32_e32 v38, v0
	v_mov_b32_e32 v39, v0
	v_mov_b32_e32 v48, v0
	v_mov_b32_e32 v49, v0
	v_mov_b32_e32 v50, v0
	v_mov_b32_e32 v51, v0
	v_mov_b32_e32 v52, v0
	v_mov_b32_e32 v53, v0
	v_mov_b32_e32 v54, v0
	v_mov_b32_e32 v55, v0
	v_mov_b32_e32 v8, v0
	v_mov_b32_e32 v9, v0
	v_mov_b32_e32 v10, v0
	v_mov_b32_e32 v11, v0
	v_mov_b32_e32 v12, v0
	v_mov_b32_e32 v13, v0
	v_mov_b32_e32 v14, v0
	v_mov_b32_e32 v15, v0
	v_mov_b32_e32 v24, v0
	v_mov_b32_e32 v25, v0
	v_mov_b32_e32 v26, v0
	v_mov_b32_e32 v27, v0
	v_mov_b32_e32 v28, v0
	v_mov_b32_e32 v29, v0
	v_mov_b32_e32 v30, v0
	v_mov_b32_e32 v31, v0
	v_mov_b32_e32 v40, v0
	v_mov_b32_e32 v41, v0
	v_mov_b32_e32 v42, v0
	v_mov_b32_e32 v43, v0
	v_mov_b32_e32 v44, v0
	v_mov_b32_e32 v45, v0
	v_mov_b32_e32 v46, v0
	v_mov_b32_e32 v47, v0
	v_mov_b32_e32 v56, v0
	v_mov_b32_e32 v57, v0
	v_mov_b32_e32 v58, v0
	v_mov_b32_e32 v59, v0
	v_mov_b32_e32 v60, v0
	v_mov_b32_e32 v61, v0
	v_mov_b32_e32 v62, v0
	v_mov_b32_e32 v63, v0
	v_mov_b32_e32 v64, v0
	v_mov_b32_e32 v65, v0
	v_mov_b32_e32 v66, v0
	v_mov_b32_e32 v67, v0
	v_mov_b32_e32 v68, v0
	v_mov_b32_e32 v69, v0
	v_mov_b32_e32 v70, v0
	v_mov_b32_e32 v71, v0
	v_mov_b32_e32 v80, v0
	v_mov_b32_e32 v81, v0
	v_mov_b32_e32 v82, v0
	v_mov_b32_e32 v83, v0
	v_mov_b32_e32 v84, v0
	v_mov_b32_e32 v85, v0
	v_mov_b32_e32 v86, v0
	v_mov_b32_e32 v87, v0
	v_mov_b32_e32 v96, v0
	v_mov_b32_e32 v97, v0
	v_mov_b32_e32 v98, v0
	v_mov_b32_e32 v99, v0
	v_mov_b32_e32 v100, v0
	v_mov_b32_e32 v101, v0
	v_mov_b32_e32 v102, v0
	v_mov_b32_e32 v103, v0
	v_mov_b32_e32 v112, v0
	v_mov_b32_e32 v113, v0
	v_mov_b32_e32 v114, v0
	v_mov_b32_e32 v115, v0
	v_mov_b32_e32 v116, v0
	v_mov_b32_e32 v117, v0
	v_mov_b32_e32 v118, v0
	v_mov_b32_e32 v119, v0
	v_mov_b32_e32 v72, v0
	v_mov_b32_e32 v73, v0
	v_mov_b32_e32 v74, v0
	v_mov_b32_e32 v75, v0
	v_mov_b32_e32 v76, v0
	v_mov_b32_e32 v77, v0
	v_mov_b32_e32 v78, v0
	v_mov_b32_e32 v79, v0
	v_mov_b32_e32 v88, v0
	v_mov_b32_e32 v89, v0
	v_mov_b32_e32 v90, v0
	v_mov_b32_e32 v91, v0
	v_mov_b32_e32 v92, v0
	v_mov_b32_e32 v93, v0
	v_mov_b32_e32 v94, v0
	v_mov_b32_e32 v95, v0
	v_mov_b32_e32 v104, v0
	v_mov_b32_e32 v105, v0
	v_mov_b32_e32 v106, v0
	v_mov_b32_e32 v107, v0
	v_mov_b32_e32 v108, v0
	v_mov_b32_e32 v109, v0
	v_mov_b32_e32 v110, v0
	v_mov_b32_e32 v111, v0
	v_mov_b32_e32 v120, v0
	v_mov_b32_e32 v121, v0
	v_mov_b32_e32 v122, v0
	v_mov_b32_e32 v123, v0
	v_mov_b32_e32 v124, v0
	v_mov_b32_e32 v125, v0
	v_mov_b32_e32 v126, v0
	v_mov_b32_e32 v127, v0
	s_cmp_lg_u32 s80, 0
	s_cbranch_scc0 .LBB0_1435
	ds_read_b128 v[136:139], v161
	ds_read_b128 v[140:143], v161 offset:16
	ds_read_b128 v[168:171], v161 offset:2048
	ds_read_b128 v[172:175], v161 offset:2064
	ds_read_b128 v[176:179], v162
	ds_read_b128 v[180:183], v162 offset:16
	ds_read_b128 v[184:187], v162 offset:2048
	ds_read_b128 v[188:191], v162 offset:2064
	s_add_i32 s9, s6, 0xfffc0080
	s_cmp_eq_u32 s8, 12
	s_cselect_b32 s11, s0, s9
	s_cselect_b32 s10, s1, s7
	s_or_b32 s9, s11, 0x80
	s_mov_b32 m0, s64
	ds_read_b128 v[192:195], v163
	ds_read_b128 v[196:199], v163 offset:16
	ds_read_b128 v[200:203], v163 offset:2048
	ds_read_b128 v[204:207], v163 offset:2064
	ds_read_b128 v[208:211], v163 offset:4096
	ds_read_b128 v[212:215], v163 offset:4112
	ds_read_b128 v[216:219], v163 offset:6144
	ds_read_b128 v[220:223], v163 offset:6160
	buffer_load_dwordx4 v252, s[28:31], s6 offen lds
	s_mov_b32 m0, s66
	s_nop 0
	buffer_load_dwordx4 v159, s[28:31], s6 offen lds
	s_waitcnt vmcnt(24)
	s_waitcnt lgkmcnt(0)
	s_barrier
	s_setprio 1
	s_waitcnt lgkmcnt(6)
	v_mfma_f32_16x16x128_f8f6f4 v[124:127], v[136:143], v[192:199], v[124:127]
	v_mfma_f32_16x16x128_f8f6f4 v[120:123], v[168:175], v[192:199], v[120:123]
	s_waitcnt lgkmcnt(4)
	v_mfma_f32_16x16x128_f8f6f4 v[108:111], v[136:143], v[200:207], v[108:111]
	v_mfma_f32_16x16x128_f8f6f4 v[104:107], v[168:175], v[200:207], v[104:107]
	s_waitcnt lgkmcnt(2)
	v_mfma_f32_16x16x128_f8f6f4 v[128:131], v[136:143], v[208:215], v[92:95]
	v_mfma_f32_16x16x128_f8f6f4 v[144:147], v[168:175], v[208:215], v[88:91]
	s_waitcnt lgkmcnt(0)
	v_mfma_f32_16x16x128_f8f6f4 v[150:153], v[136:143], v[216:223], v[76:79]
	v_mfma_f32_16x16x128_f8f6f4 v[224:227], v[168:175], v[216:223], v[72:75]
	s_setprio 0
	s_setprio 1
	v_mfma_f32_16x16x128_f8f6f4 v[116:119], v[176:183], v[192:199], v[116:119]
	v_mfma_f32_16x16x128_f8f6f4 v[112:115], v[184:191], v[192:199], v[112:115]
	v_mfma_f32_16x16x128_f8f6f4 v[100:103], v[176:183], v[200:207], v[100:103]
	v_mfma_f32_16x16x128_f8f6f4 v[96:99], v[184:191], v[200:207], v[96:99]
	v_mfma_f32_16x16x128_f8f6f4 v[192:195], v[176:183], v[208:215], v[84:87]
	v_mfma_f32_16x16x128_f8f6f4 v[196:199], v[184:191], v[208:215], v[80:83]
	v_mfma_f32_16x16x128_f8f6f4 v[200:203], v[176:183], v[216:223], v[68:71]
	v_mfma_f32_16x16x128_f8f6f4 v[204:207], v[184:191], v[216:223], v[64:67]
	s_setprio 0
	s_barrier
; #define PG8_STAGE_A(bufoff, off) PG8_STAGE_X(bufoff, rsA, g.A, off, voffA)
; #define PG8_STAGE_B(bufoff, off) PG8_STAGE_X(bufoff, rsB, g.Bt, off, voffB)
; #define PG8_LDA(dst, b, h) do { _Pragma("unroll") for (int m = 0; m < 4; ++m) _Pragma("unroll") for (int k = 0; k < 2; ++k) { const v4i_t f_ = *(const LAS v4i_t*)(lds + PG8_SA(b, h) + aoff + m * 2048 + k * KOFF); dst[m][4 * k] = f_[0]; dst[m][4 * k + 1] = f_[1]; dst[m][4 * k + 2] = f_[2]; dst[m][4 * k + 3] = f_[3]; } } while (0)
; #define PG8_LDB(dst, b, h) do { _Pragma("unroll") for (int n = 0; n < 2; ++n) _Pragma("unroll") for (int k = 0; k < 2; ++k) { const v4i_t f_ = *(const LAS v4i_t*)(lds + PG8_SB(b, h) + boff + n * 2048 + k * KOFF); dst[n][4 * k] = f_[0]; dst[n][4 * k + 1] = f_[1]; dst[n][4 * k + 2] = f_[2]; dst[n][4 * k + 3] = f_[3]; } } while (0)
; #define PG8_WAIT_V(n) asm volatile("s_waitcnt vmcnt(" #n ")" ::: "memory")
; #define PG8_WAIT_L(n) asm volatile("s_waitcnt lgkmcnt(" #n ")" ::: "memory")
; #define PG8_BAR __builtin_amdgcn_s_barrier()
; #define PG8_SCHED __builtin_amdgcn_sched_barrier(0)
; template <class Epi, class Sched, bool ALIGN_EPI, bool F8 = false>
; __device__ __forceinline__ void gemm_phase(LAS unsigned char* lds, const Gemm g, const Sched& S, const Epi& E) {
;     ...
;             PG8_LDA(At, 0, 1); PG8_STAGE_B(PG8_SB(0, 0), b2); PG8_STAGE_B(PG8_SB(0, 1), b2 + hstepB); PG8_STAGE_A(PG8_SA(0, 0), a2);
;             PG8_WAIT_V(8); PG8_WAIT_L(0); PG8_BAR; PG8_MMA(1, 0, At, B0); PG8_MMA(1, 1, At, B1); PG8_BAR; PG8_SCHED;
;             PG8_LDB(B0, 1, 0); PG8_LDB(B1, 1, 1); PG8_SCHED; PG8_LDA(At, 1, 0); PG8_STAGE_A(PG8_SA(0, 1), a2 + hstepA);
;             PG8_WAIT_V(8); PG8_WAIT_L(0); PG8_BAR; PG8_MMA(0, 0, At, B0); PG8_MMA(0, 1, At, B1); PG8_BAR; PG8_SCHED;
;             PG8_LDA(At, 1, 1); PG8_STAGE_B(PG8_SB(1, 0), b3); PG8_STAGE_B(PG8_SB(1, 1), b3 + hstepB); PG8_STAGE_A(PG8_SA(1, 0), a3);
;             PG8_WAIT_V(8); PG8_WAIT_L(0); PG8_BAR; PG8_MMA(1, 0, At, B0); PG8_MMA(1, 1, At, B1); PG8_BAR; PG8_SCHED;
	s_mov_b32 m0, s38
	s_mov_b32 s26, s30
	s_mov_b32 s27, s31
	s_nop 1
	ds_read_b128 v[64:67], v163 offset:16384
	ds_read_b128 v[68:71], v163 offset:16400
	ds_read_b128 v[72:75], v163 offset:18432
	ds_read_b128 v[76:79], v163 offset:18448
	ds_read_b128 v[80:83], v163 offset:20480
	ds_read_b128 v[84:87], v163 offset:20496
	ds_read_b128 v[88:91], v163 offset:22528
	ds_read_b128 v[92:95], v163 offset:22544
	buffer_load_dwordx4 v158, s[24:27], s10 offen lds
	s_mov_b32 m0, s39
	s_add_i32 s12, s10, 0x40000
	buffer_load_dwordx4 v160, s[24:27], s10 offen lds
	s_mov_b32 m0, s40
	s_nop 0
	buffer_load_dwordx4 v158, s[24:27], s12 offen lds
	s_mov_b32 m0, s41
	s_nop 0
	buffer_load_dwordx4 v160, s[24:27], s12 offen lds
	s_mov_b32 m0, s37
	s_nop 0
	buffer_load_dwordx4 v252, s[28:31], s11 offen lds
	s_mov_b32 m0, s42
	s_nop 0
	buffer_load_dwordx4 v159, s[28:31], s11 offen lds
	s_waitcnt vmcnt(24)
	s_waitcnt lgkmcnt(0)
	s_barrier
	s_setprio 1
	s_waitcnt lgkmcnt(6)
	v_mfma_f32_16x16x128_f8f6f4 v[60:63], v[136:143], v[64:71], v[60:63]
	v_mfma_f32_16x16x128_f8f6f4 v[56:59], v[168:175], v[64:71], v[56:59]
	s_waitcnt lgkmcnt(4)
	v_mfma_f32_16x16x128_f8f6f4 v[208:211], v[136:143], v[72:79], v[44:47]
	v_mfma_f32_16x16x128_f8f6f4 v[212:215], v[168:175], v[72:79], v[40:43]
	s_waitcnt lgkmcnt(2)
	v_mfma_f32_16x16x128_f8f6f4 v[216:219], v[136:143], v[80:87], v[28:31]
	v_mfma_f32_16x16x128_f8f6f4 v[220:223], v[168:175], v[80:87], v[24:27]
	s_waitcnt lgkmcnt(0)
	v_mfma_f32_16x16x128_f8f6f4 v[228:231], v[136:143], v[88:95], v[12:15]
	v_mfma_f32_16x16x128_f8f6f4 v[232:235], v[168:175], v[88:95], v[8:11]
	s_setprio 0
	s_setprio 1
	v_mfma_f32_16x16x128_f8f6f4 v[52:55], v[176:183], v[64:71], v[52:55]
	v_mfma_f32_16x16x128_f8f6f4 v[48:51], v[184:191], v[64:71], v[48:51]
	v_mfma_f32_16x16x128_f8f6f4 v[236:239], v[176:183], v[72:79], v[36:39]
	v_mfma_f32_16x16x128_f8f6f4 v[240:243], v[184:191], v[72:79], v[32:35]
	v_mfma_f32_16x16x128_f8f6f4 v[244:247], v[176:183], v[80:87], v[20:23]
	v_mfma_f32_16x16x128_f8f6f4 v[248:251], v[184:191], v[80:87], v[16:19]
	v_mfma_f32_16x16x128_f8f6f4 v[132:135], v[176:183], v[88:95], v[4:7]
	v_mfma_f32_16x16x128_f8f6f4 v[154:157], v[184:191], v[88:95], v[0:3]
	s_setprio 0
	s_barrier
	s_nop 4
	ds_read_b128 v[0:3], v164
	ds_read_b128 v[4:7], v164 offset:16
	ds_read_b128 v[16:19], v164 offset:2048
	ds_read_b128 v[20:23], v164 offset:2064
	ds_read_b128 v[136:139], v165
	ds_read_b128 v[140:143], v165 offset:16
	ds_read_b128 v[168:171], v165 offset:2048
	ds_read_b128 v[172:175], v165 offset:2064
	s_add_i32 s11, s11, 0x40000
	s_mov_b32 m0, s43
	ds_read_b128 v[8:11], v163 offset:32768
	ds_read_b128 v[12:15], v163 offset:32784
	ds_read_b128 v[24:27], v163 offset:34816
	ds_read_b128 v[28:31], v163 offset:34832
	ds_read_b128 v[32:35], v163 offset:36864
	ds_read_b128 v[36:39], v163 offset:36880
	ds_read_b128 v[40:43], v163 offset:38912
	ds_read_b128 v[44:47], v163 offset:38928
	buffer_load_dwordx4 v252, s[28:31], s11 offen lds
	s_mov_b32 m0, s54
	s_nop 0
	buffer_load_dwordx4 v159, s[28:31], s11 offen lds
	s_waitcnt vmcnt(8)
	s_waitcnt lgkmcnt(0)
	s_barrier
	s_setprio 1
	s_waitcnt lgkmcnt(6)
	v_mfma_f32_16x16x128_f8f6f4 v[124:127], v[0:7], v[8:15], v[124:127]
	v_mfma_f32_16x16x128_f8f6f4 v[120:123], v[16:23], v[8:15], v[120:123]
	s_waitcnt lgkmcnt(4)
	v_mfma_f32_16x16x128_f8f6f4 v[108:111], v[0:7], v[24:31], v[108:111]
	v_mfma_f32_16x16x128_f8f6f4 v[104:107], v[16:23], v[24:31], v[104:107]
	s_waitcnt lgkmcnt(2)
	v_mfma_f32_16x16x128_f8f6f4 v[92:95], v[0:7], v[32:39], v[128:131]
	v_mfma_f32_16x16x128_f8f6f4 v[88:91], v[16:23], v[32:39], v[144:147]
	s_waitcnt lgkmcnt(0)
	v_mfma_f32_16x16x128_f8f6f4 v[76:79], v[0:7], v[40:47], v[150:153]
	v_mfma_f32_16x16x128_f8f6f4 v[72:75], v[16:23], v[40:47], v[224:227]
	s_setprio 0
	s_setprio 1
	v_mfma_f32_16x16x128_f8f6f4 v[116:119], v[136:143], v[8:15], v[116:119]
	v_mfma_f32_16x16x128_f8f6f4 v[112:115], v[168:175], v[8:15], v[112:115]
	v_mfma_f32_16x16x128_f8f6f4 v[100:103], v[136:143], v[24:31], v[100:103]
	v_mfma_f32_16x16x128_f8f6f4 v[96:99], v[168:175], v[24:31], v[96:99]
	v_mfma_f32_16x16x128_f8f6f4 v[84:87], v[136:143], v[32:39], v[192:195]
	v_mfma_f32_16x16x128_f8f6f4 v[80:83], v[168:175], v[32:39], v[196:199]
	v_mfma_f32_16x16x128_f8f6f4 v[68:71], v[136:143], v[40:47], v[200:203]
	v_mfma_f32_16x16x128_f8f6f4 v[64:67], v[168:175], v[40:47], v[204:207]
	s_setprio 0
	s_barrier
	s_mov_b32 m0, s55
	s_or_b32 s11, s10, 0x80
	ds_read_b128 v[32:35], v163 offset:49152
	ds_read_b128 v[36:39], v163 offset:49168
	ds_read_b128 v[176:179], v163 offset:51200
	ds_read_b128 v[180:183], v163 offset:51216
	ds_read_b128 v[184:187], v163 offset:53248
	ds_read_b128 v[188:191], v163 offset:53264
	ds_read_b128 v[192:195], v163 offset:55296
	ds_read_b128 v[196:199], v163 offset:55312
	buffer_load_dwordx4 v158, s[24:27], s11 offen lds
	s_mov_b32 m0, s56
	s_add_i32 s10, s10, 0x40080
	buffer_load_dwordx4 v160, s[24:27], s11 offen lds
	s_mov_b32 m0, s59
	s_nop 0
	buffer_load_dwordx4 v158, s[24:27], s10 offen lds
	s_mov_b32 m0, s60
	s_nop 0
	buffer_load_dwordx4 v160, s[24:27], s10 offen lds
	s_mov_b32 m0, s57
	s_nop 0
	buffer_load_dwordx4 v252, s[28:31], s9 offen lds
	s_mov_b32 m0, s58
	s_nop 0
	buffer_load_dwordx4 v159, s[28:31], s9 offen lds
	s_waitcnt vmcnt(8)
	s_waitcnt lgkmcnt(0)
	s_barrier
	s_setprio 1
	s_waitcnt lgkmcnt(6)
	v_mfma_f32_16x16x128_f8f6f4 v[60:63], v[0:7], v[32:39], v[60:63]
	v_mfma_f32_16x16x128_f8f6f4 v[56:59], v[16:23], v[32:39], v[56:59]
	s_waitcnt lgkmcnt(4)
	v_mfma_f32_16x16x128_f8f6f4 v[44:47], v[0:7], v[176:183], v[208:211]
	v_mfma_f32_16x16x128_f8f6f4 v[40:43], v[16:23], v[176:183], v[212:215]
	s_waitcnt lgkmcnt(2)
	v_mfma_f32_16x16x128_f8f6f4 v[28:31], v[0:7], v[184:191], v[216:219]
	v_mfma_f32_16x16x128_f8f6f4 v[24:27], v[16:23], v[184:191], v[220:223]
	s_waitcnt lgkmcnt(0)
	v_mfma_f32_16x16x128_f8f6f4 v[12:15], v[0:7], v[192:199], v[228:231]
	v_mfma_f32_16x16x128_f8f6f4 v[8:11], v[16:23], v[192:199], v[232:235]
	s_setprio 0
	s_setprio 1
	v_mfma_f32_16x16x128_f8f6f4 v[52:55], v[136:143], v[32:39], v[52:55]
	v_mfma_f32_16x16x128_f8f6f4 v[48:51], v[168:175], v[32:39], v[48:51]
	v_mfma_f32_16x16x128_f8f6f4 v[36:39], v[136:143], v[176:183], v[236:239]
	v_mfma_f32_16x16x128_f8f6f4 v[32:35], v[168:175], v[176:183], v[240:243]
	v_mfma_f32_16x16x128_f8f6f4 v[20:23], v[136:143], v[184:191], v[244:247]
	v_mfma_f32_16x16x128_f8f6f4 v[16:19], v[168:175], v[184:191], v[248:251]
	v_mfma_f32_16x16x128_f8f6f4 v[4:7], v[136:143], v[192:199], v[132:135]
	v_mfma_f32_16x16x128_f8f6f4 v[0:3], v[168:175], v[192:199], v[154:157]
	s_setprio 0
	s_barrier
	s_add_i32 s8, s8, 2
	s_addk_i32 s6, 0x100
	s_addk_i32 s7, 0x100
	s_cmp_gt_u32 s8, 13
	s_cbranch_scc0 .LBB0_1435
	s_branch .Lpeel_after_pl1
